# baseline (speedup 1.0000x reference)
; __device__ __forceinline__ unsigned cvt_pk_bf16(float lo, float hi) { unsigned r; asm volatile("v_cvt_pk_bf16_f32 %0, %1, %2" : "=v"(r) : "v"(lo), "v"(hi)); return r; }
; __device__ __forceinline__ float sigmoidf_(float x) { return __builtin_amdgcn_rcpf(1.0f + __expf(-x)); }
;     __device__ __forceinline__ void operator()(const f32x4 (&acc)[2][2][4][2], const Unit& u, int wr, int wc, int fr, int fq) const {
;     ...
;             for (int m = 0; m < 4; ++m) { const size_t row = (size_t)(row0 + ai * HALF + m * 16);
; #pragma unroll
;                 for (int bj = 0; bj < 2; ++bj) { const int c = col0 + bj * HALF;
;                     const u32x4 yv = *(const u32x4*)(Y + row * ldy + c);
;                     const f32x4 v0 = acc[ai][bj][m][0], v1 = acc[ai][bj][m][1];
;                     u32x4 w;
;                     w.x = cvt_pk_bf16(bflo(yv.x) * sigmoidf_(v0[0]), bfhi(yv.x) * sigmoidf_(v0[1]));
;                     w.y = cvt_pk_bf16(bflo(yv.y) * sigmoidf_(v0[2]), bfhi(yv.y) * sigmoidf_(v0[3]));
;                     w.z = cvt_pk_bf16(bflo(yv.z) * sigmoidf_(v1[0]), bfhi(yv.z) * sigmoidf_(v1[1]));
;                     w.w = cvt_pk_bf16(bflo(yv.w) * sigmoidf_(v1[2]), bfhi(yv.w) * sigmoidf_(v1[3]));
;                     *(u32x4*)(O + row * ldc + ocol0 + c) = w; } }
.LBB0_398:
	s_lshl_b32 s13, s20, 8
	v_mov_b32_e32 v138, v142
	v_mov_b32_e32 v139, v143
	s_add_i32 s13, s13, s59
	s_nop 7
	s_nop 7
	v_mul_f32_e32 v124, 0xbfb8aa3b, v124
	v_add_u32_e32 v140, s13, v138
	s_lshl_b32 s13, s65, 8
	s_or_b32 s13, s13, s60
	v_lshl_add_u32 v138, v139, 3, s13
	v_ashrrev_i32_e32 v141, 31, v140
	v_lshlrev_b64 v[146:147], 10, v[140:141]
	v_ashrrev_i32_e32 v139, 31, v138
	v_lshl_add_u64 v[146:147], s[6:7], 0, v[146:147]
	v_lshlrev_b64 v[138:139], 1, v[138:139]
	v_lshl_add_u64 v[150:151], v[146:147], 0, v[138:139]
	global_load_dwordx4 v[146:149], v[150:151], off
	v_mul_f32_e32 v125, 0xbfb8aa3b, v125
	v_mul_f32_e32 v123, 0xbfb8aa3b, v123
	v_mul_f32_e32 v126, 0xbfb8aa3b, v126
	v_mul_f32_e32 v127, 0xbfb8aa3b, v127
	v_mul_f32_e32 v120, 0xbfb8aa3b, v120
	v_mul_f32_e32 v121, 0xbfb8aa3b, v121
	v_mul_f32_e32 v122, 0xbfb8aa3b, v122
	v_exp_f32_e32 v124, v124
	v_exp_f32_e32 v125, v125
	v_exp_f32_e32 v123, v123
	v_exp_f32_e32 v126, v126
	v_exp_f32_e32 v127, v127
	v_exp_f32_e32 v170, v120
	v_exp_f32_e32 v171, v121
	v_exp_f32_e32 v122, v122
	v_add_f32_e32 v124, 1.0, v124
	v_add_f32_e32 v125, 1.0, v125
	v_add_f32_e32 v123, 1.0, v123
	v_lshlrev_b64 v[120:121], 12, v[140:141]
	v_add_f32_e32 v126, 1.0, v126
	v_add_f32_e32 v127, 1.0, v127
	v_add_f32_e32 v141, 1.0, v170
	v_add_f32_e32 v170, 1.0, v171
	v_add_f32_e32 v122, 1.0, v122
	v_rcp_f32_e32 v171, v124
	v_rcp_f32_e32 v172, v125
	v_rcp_f32_e32 v123, v123
	v_rcp_f32_e32 v126, v126
	v_rcp_f32_e32 v127, v127
	v_rcp_f32_e32 v141, v141
	v_rcp_f32_e32 v170, v170
	v_rcp_f32_e32 v122, v122
	v_lshl_add_u64 v[120:121], s[8:9], 0, v[120:121]
	v_lshl_add_u64 v[124:125], v[120:121], 0, v[138:139]
	v_mul_f32_e32 v116, 0xbfb8aa3b, v116
	v_mul_f32_e32 v117, 0xbfb8aa3b, v117
	v_mul_f32_e32 v115, 0xbfb8aa3b, v115
	v_mul_f32_e32 v118, 0xbfb8aa3b, v118
	v_mul_f32_e32 v119, 0xbfb8aa3b, v119
	v_mul_f32_e32 v112, 0xbfb8aa3b, v112
	v_mul_f32_e32 v113, 0xbfb8aa3b, v113
	v_mul_f32_e32 v114, 0xbfb8aa3b, v114
	v_exp_f32_e32 v115, v115
	v_exp_f32_e32 v118, v118
	v_exp_f32_e32 v119, v119
	v_exp_f32_e32 v112, v112
	v_exp_f32_e32 v113, v113
	v_exp_f32_e32 v114, v114
	v_add_f32_e32 v115, 1.0, v115
	v_add_f32_e32 v118, 1.0, v118
	v_add_f32_e32 v119, 1.0, v119
	v_add_f32_e32 v114, 1.0, v114
	v_rcp_f32_e32 v115, v115
	v_rcp_f32_e32 v114, v114
	v_mul_f32_e32 v108, 0xbfb8aa3b, v108
	v_mul_f32_e32 v109, 0xbfb8aa3b, v109
	v_mul_f32_e32 v107, 0xbfb8aa3b, v107
	v_mul_f32_e32 v110, 0xbfb8aa3b, v110
	v_mul_f32_e32 v111, 0xbfb8aa3b, v111
	v_mul_f32_e32 v104, 0xbfb8aa3b, v104
	v_mul_f32_e32 v105, 0xbfb8aa3b, v105
	v_mul_f32_e32 v106, 0xbfb8aa3b, v106
	v_exp_f32_e32 v108, v108
	v_exp_f32_e32 v109, v109
	v_exp_f32_e32 v107, v107
	v_exp_f32_e32 v110, v110
	v_exp_f32_e32 v111, v111
	v_exp_f32_e32 v104, v104
	v_exp_f32_e32 v105, v105
	v_exp_f32_e32 v106, v106
	v_add_f32_e32 v108, 1.0, v108
	v_add_f32_e32 v109, 1.0, v109
	v_add_f32_e32 v107, 1.0, v107
	v_add_f32_e32 v110, 1.0, v110
	v_add_f32_e32 v111, 1.0, v111
	v_add_f32_e32 v106, 1.0, v106
	v_rcp_f32_e32 v107, v107
	v_rcp_f32_e32 v110, v110
	v_rcp_f32_e32 v111, v111
	s_waitcnt vmcnt(0)
	v_lshlrev_b32_e32 v120, 16, v146
	v_and_b32_e32 v121, 0xffff0000, v146
	v_lshlrev_b32_e32 v174, 16, v149
	v_and_b32_e32 v149, 0xffff0000, v149
	v_lshlrev_b32_e32 v146, 16, v147
	v_and_b32_e32 v147, 0xffff0000, v147
	v_lshlrev_b32_e32 v173, 16, v148
	v_and_b32_e32 v148, 0xffff0000, v148
	v_mul_f32_e32 v120, v171, v120
	v_mul_f32_e32 v121, v172, v121
	v_mul_f32_e32 v123, v123, v149
	v_mul_f32_e32 v126, v126, v146
	v_mul_f32_e32 v127, v127, v147
	v_mul_f32_e32 v141, v141, v173
	v_mul_f32_e32 v146, v170, v148
	v_mul_f32_e32 v147, v122, v174
	v_cvt_pk_bf16_f32 v120, v120, v121
	v_cvt_pk_bf16_f32 v121, v126, v127
	v_cvt_pk_bf16_f32 v122, v141, v146
	v_cvt_pk_bf16_f32 v123, v147, v123
	global_store_dwordx4 v[124:125], v[120:123], off offset:2048
	global_load_dwordx4 v[120:123], v[150:151], off offset:256
	v_exp_f32_e32 v126, v116
	v_exp_f32_e32 v127, v117
	v_add_u32_e32 v116, 16, v140
	v_ashrrev_i32_e32 v117, 31, v116
	v_add_f32_e32 v126, 1.0, v126
	v_add_f32_e32 v127, 1.0, v127
	v_add_f32_e32 v141, 1.0, v112
	v_add_f32_e32 v146, 1.0, v113
	v_rcp_f32_e32 v126, v126
	v_rcp_f32_e32 v127, v127
	v_lshlrev_b64 v[112:113], 10, v[116:117]
	v_rcp_f32_e32 v147, v118
	v_rcp_f32_e32 v148, v119
	v_rcp_f32_e32 v141, v141
	v_rcp_f32_e32 v146, v146
	v_lshl_add_u64 v[112:113], s[6:7], 0, v[112:113]
	v_lshl_add_u64 v[118:119], v[112:113], 0, v[138:139]
	v_rcp_f32_e32 v106, v106
	v_mul_f32_e32 v100, 0xbfb8aa3b, v100
	v_mul_f32_e32 v101, 0xbfb8aa3b, v101
	v_mul_f32_e32 v99, 0xbfb8aa3b, v99
	v_mul_f32_e32 v102, 0xbfb8aa3b, v102
	v_mul_f32_e32 v103, 0xbfb8aa3b, v103
	v_mul_f32_e32 v96, 0xbfb8aa3b, v96
	v_mul_f32_e32 v97, 0xbfb8aa3b, v97
	v_mul_f32_e32 v98, 0xbfb8aa3b, v98
	v_exp_f32_e32 v99, v99
	v_exp_f32_e32 v102, v102
	v_exp_f32_e32 v103, v103
	v_exp_f32_e32 v96, v96
	v_exp_f32_e32 v97, v97
	v_exp_f32_e32 v98, v98
	v_add_f32_e32 v99, 1.0, v99
	v_add_f32_e32 v102, 1.0, v102
	v_add_f32_e32 v103, 1.0, v103
	v_add_f32_e32 v98, 1.0, v98
	v_rcp_f32_e32 v99, v99
	v_rcp_f32_e32 v98, v98
	v_mul_f32_e32 v92, 0xbfb8aa3b, v92
	v_mul_f32_e32 v93, 0xbfb8aa3b, v93
	v_mul_f32_e32 v91, 0xbfb8aa3b, v91
	v_mul_f32_e32 v94, 0xbfb8aa3b, v94
	v_mul_f32_e32 v95, 0xbfb8aa3b, v95
	v_mul_f32_e32 v88, 0xbfb8aa3b, v88
	v_mul_f32_e32 v89, 0xbfb8aa3b, v89
	v_mul_f32_e32 v90, 0xbfb8aa3b, v90
	v_exp_f32_e32 v92, v92
	v_exp_f32_e32 v93, v93
	v_exp_f32_e32 v91, v91
	v_exp_f32_e32 v94, v94
	v_exp_f32_e32 v95, v95
	v_exp_f32_e32 v88, v88
	v_exp_f32_e32 v89, v89
	v_exp_f32_e32 v90, v90
	v_add_f32_e32 v92, 1.0, v92
	v_add_f32_e32 v93, 1.0, v93
	v_add_f32_e32 v91, 1.0, v91
	v_add_f32_e32 v94, 1.0, v94
	v_add_f32_e32 v95, 1.0, v95
	v_add_f32_e32 v90, 1.0, v90
	v_rcp_f32_e32 v91, v91
	v_rcp_f32_e32 v94, v94
	v_rcp_f32_e32 v95, v95
	v_rcp_f32_e32 v90, v90
	v_mul_f32_e32 v84, 0xbfb8aa3b, v84
	v_mul_f32_e32 v85, 0xbfb8aa3b, v85
	v_mul_f32_e32 v83, 0xbfb8aa3b, v83
	v_mul_f32_e32 v86, 0xbfb8aa3b, v86
	v_mul_f32_e32 v87, 0xbfb8aa3b, v87
	v_mul_f32_e32 v80, 0xbfb8aa3b, v80
	v_mul_f32_e32 v81, 0xbfb8aa3b, v81
	v_mul_f32_e32 v82, 0xbfb8aa3b, v82
	v_exp_f32_e32 v83, v83
	v_exp_f32_e32 v86, v86
	v_exp_f32_e32 v87, v87
	v_exp_f32_e32 v80, v80
	v_exp_f32_e32 v81, v81
	v_exp_f32_e32 v82, v82
	v_add_f32_e32 v83, 1.0, v83
	s_waitcnt vmcnt(0)
; __device__ __forceinline__ unsigned cvt_pk_bf16(float lo, float hi) { unsigned r; asm volatile("v_cvt_pk_bf16_f32 %0, %1, %2" : "=v"(r) : "v"(lo), "v"(hi)); return r; }
; __device__ __forceinline__ float sigmoidf_(float x) { return __builtin_amdgcn_rcpf(1.0f + __expf(-x)); }
;     __device__ __forceinline__ void operator()(const f32x4 (&acc)[2][2][4][2], const Unit& u, int wr, int wc, int fr, int fq) const {
;     ...
;             for (int m = 0; m < 4; ++m) { const size_t row = (size_t)(row0 + ai * HALF + m * 16);
; #pragma unroll
;                 for (int bj = 0; bj < 2; ++bj) { const int c = col0 + bj * HALF;
;                     const u32x4 yv = *(const u32x4*)(Y + row * ldy + c);
;                     const f32x4 v0 = acc[ai][bj][m][0], v1 = acc[ai][bj][m][1];
;                     u32x4 w;
;                     w.x = cvt_pk_bf16(bflo(yv.x) * sigmoidf_(v0[0]), bfhi(yv.x) * sigmoidf_(v0[1]));
;                     w.y = cvt_pk_bf16(bflo(yv.y) * sigmoidf_(v0[2]), bfhi(yv.y) * sigmoidf_(v0[3]));
;                     w.z = cvt_pk_bf16(bflo(yv.z) * sigmoidf_(v1[0]), bfhi(yv.z) * sigmoidf_(v1[1]));
;                     w.w = cvt_pk_bf16(bflo(yv.w) * sigmoidf_(v1[2]), bfhi(yv.w) * sigmoidf_(v1[3]));
;                     *(u32x4*)(O + row * ldc + ocol0 + c) = w; } }
	v_lshlrev_b32_e32 v112, 16, v120
	v_and_b32_e32 v113, 0xffff0000, v120
	v_lshlrev_b32_e32 v150, 16, v123
	v_and_b32_e32 v123, 0xffff0000, v123
	v_lshlrev_b32_e32 v120, 16, v121
	v_and_b32_e32 v121, 0xffff0000, v121
	v_lshlrev_b32_e32 v149, 16, v122
	v_and_b32_e32 v122, 0xffff0000, v122
	v_mul_f32_e32 v112, v126, v112
	v_mul_f32_e32 v113, v127, v113
	v_mul_f32_e32 v115, v115, v123
	v_mul_f32_e32 v120, v147, v120
	v_mul_f32_e32 v121, v148, v121
	v_mul_f32_e32 v126, v141, v149
	v_mul_f32_e32 v122, v146, v122
	v_mul_f32_e32 v127, v114, v150
	v_cvt_pk_bf16_f32 v112, v112, v113
	v_cvt_pk_bf16_f32 v113, v120, v121
	v_cvt_pk_bf16_f32 v114, v126, v122
	v_cvt_pk_bf16_f32 v115, v127, v115
	global_store_dwordx4 v[124:125], v[112:115], off offset:2304
	global_load_dwordx4 v[112:115], v[118:119], off
	global_load_dwordx4 v[172:175], v[118:119], off offset:256
	v_add_u32_e32 v170, 32, v140
	v_ashrrev_i32_e32 v171, 31, v170
	v_lshlrev_b64 v[170:171], 10, v[170:171]
	v_lshl_add_u64 v[170:171], s[6:7], 0, v[170:171]
	v_lshl_add_u64 v[170:171], v[170:171], 0, v[138:139]
	global_load_dwordx4 v[176:179], v[170:171], off
	global_load_dwordx4 v[180:183], v[170:171], off offset:256
	v_add_u32_e32 v170, 48, v140
	v_ashrrev_i32_e32 v171, 31, v170
	v_lshlrev_b64 v[170:171], 10, v[170:171]
	v_lshl_add_u64 v[170:171], s[6:7], 0, v[170:171]
	v_lshl_add_u64 v[170:171], v[170:171], 0, v[138:139]
	global_load_dwordx4 v[184:187], v[170:171], off
	global_load_dwordx4 v[188:191], v[170:171], off offset:256
	v_add_u32_e32 v170, 0x80, v140
	v_ashrrev_i32_e32 v171, 31, v170
	v_lshlrev_b64 v[170:171], 10, v[170:171]
	v_lshl_add_u64 v[170:171], s[6:7], 0, v[170:171]
	v_lshl_add_u64 v[170:171], v[170:171], 0, v[138:139]
	global_load_dwordx4 v[200:203], v[170:171], off
	global_load_dwordx4 v[204:207], v[170:171], off offset:256
	v_add_u32_e32 v170, 0x90, v140
	v_ashrrev_i32_e32 v171, 31, v170
	v_lshlrev_b64 v[170:171], 10, v[170:171]
	v_lshl_add_u64 v[170:171], s[6:7], 0, v[170:171]
	v_lshl_add_u64 v[170:171], v[170:171], 0, v[138:139]
	global_load_dwordx4 v[208:211], v[170:171], off
	global_load_dwordx4 v[212:215], v[170:171], off offset:256
	v_add_u32_e32 v170, 0xa0, v140
	v_ashrrev_i32_e32 v171, 31, v170
	v_lshlrev_b64 v[170:171], 10, v[170:171]
	v_lshl_add_u64 v[170:171], s[6:7], 0, v[170:171]
	v_lshl_add_u64 v[170:171], v[170:171], 0, v[138:139]
	global_load_dwordx4 v[216:219], v[170:171], off
	global_load_dwordx4 v[220:223], v[170:171], off offset:256
	v_add_u32_e32 v170, 0xb0, v140
	v_ashrrev_i32_e32 v171, 31, v170
	v_lshlrev_b64 v[170:171], 10, v[170:171]
	v_lshl_add_u64 v[170:171], s[6:7], 0, v[170:171]
	v_lshl_add_u64 v[170:171], v[170:171], 0, v[138:139]
	global_load_dwordx4 v[224:227], v[170:171], off
	global_load_dwordx4 v[228:231], v[170:171], off offset:256
	v_add_f32_e32 v120, 1.0, v104
	v_add_f32_e32 v121, 1.0, v105
	v_lshlrev_b64 v[104:105], 12, v[116:117]
	v_rcp_f32_e32 v116, v108
	v_rcp_f32_e32 v117, v109
	v_rcp_f32_e32 v120, v120
	v_rcp_f32_e32 v121, v121
	v_lshl_add_u64 v[104:105], s[8:9], 0, v[104:105]
	v_lshl_add_u64 v[108:109], v[104:105], 0, v[138:139]
	v_add_f32_e32 v86, 1.0, v86
	v_add_f32_e32 v87, 1.0, v87
	v_add_f32_e32 v82, 1.0, v82
	v_rcp_f32_e32 v83, v83
	v_rcp_f32_e32 v82, v82
	v_mul_f32_e32 v76, 0xbfb8aa3b, v76
	v_mul_f32_e32 v77, 0xbfb8aa3b, v77
	v_mul_f32_e32 v75, 0xbfb8aa3b, v75
	v_mul_f32_e32 v78, 0xbfb8aa3b, v78
	v_mul_f32_e32 v79, 0xbfb8aa3b, v79
	v_mul_f32_e32 v72, 0xbfb8aa3b, v72
	v_mul_f32_e32 v73, 0xbfb8aa3b, v73
	v_mul_f32_e32 v74, 0xbfb8aa3b, v74
	v_exp_f32_e32 v76, v76
	v_exp_f32_e32 v77, v77
	v_exp_f32_e32 v75, v75
	v_exp_f32_e32 v78, v78
	v_exp_f32_e32 v79, v79
	v_exp_f32_e32 v72, v72
	v_exp_f32_e32 v73, v73
	v_exp_f32_e32 v74, v74
	v_add_f32_e32 v76, 1.0, v76
	v_add_f32_e32 v77, 1.0, v77
	v_add_f32_e32 v75, 1.0, v75
	v_add_f32_e32 v78, 1.0, v78
	v_add_f32_e32 v79, 1.0, v79
	v_add_f32_e32 v74, 1.0, v74
	v_rcp_f32_e32 v75, v75
	v_rcp_f32_e32 v78, v78
	v_rcp_f32_e32 v79, v79
	v_rcp_f32_e32 v74, v74
	v_mul_f32_e32 v68, 0xbfb8aa3b, v68
	v_mul_f32_e32 v69, 0xbfb8aa3b, v69
	v_mul_f32_e32 v67, 0xbfb8aa3b, v67
	v_mul_f32_e32 v70, 0xbfb8aa3b, v70
	v_mul_f32_e32 v71, 0xbfb8aa3b, v71
	v_mul_f32_e32 v64, 0xbfb8aa3b, v64
	v_mul_f32_e32 v65, 0xbfb8aa3b, v65
	v_mul_f32_e32 v66, 0xbfb8aa3b, v66
	v_exp_f32_e32 v67, v67
	v_exp_f32_e32 v70, v70
	v_exp_f32_e32 v71, v71
	v_exp_f32_e32 v64, v64
	v_exp_f32_e32 v65, v65
	v_exp_f32_e32 v66, v66
	v_add_f32_e32 v67, 1.0, v67
	v_add_f32_e32 v70, 1.0, v70
	v_add_f32_e32 v71, 1.0, v71
	v_add_f32_e32 v66, 1.0, v66
	v_rcp_f32_e32 v67, v67
	v_rcp_f32_e32 v66, v66
	v_mul_f32_e32 v60, 0xbfb8aa3b, v60
	v_mul_f32_e32 v61, 0xbfb8aa3b, v61
	v_mul_f32_e32 v59, 0xbfb8aa3b, v59
	v_mul_f32_e32 v62, 0xbfb8aa3b, v62
	v_mul_f32_e32 v63, 0xbfb8aa3b, v63
	v_mul_f32_e32 v56, 0xbfb8aa3b, v56
	v_mul_f32_e32 v57, 0xbfb8aa3b, v57
	v_mul_f32_e32 v58, 0xbfb8aa3b, v58
	v_exp_f32_e32 v60, v60
	v_exp_f32_e32 v61, v61
	v_exp_f32_e32 v59, v59
	v_exp_f32_e32 v62, v62
	v_exp_f32_e32 v63, v63
	v_exp_f32_e32 v56, v56
	v_exp_f32_e32 v57, v57
	v_exp_f32_e32 v58, v58
	v_add_f32_e32 v60, 1.0, v60
	v_add_f32_e32 v61, 1.0, v61
	v_add_f32_e32 v59, 1.0, v59
	s_waitcnt vmcnt(13)
; __device__ __forceinline__ unsigned cvt_pk_bf16(float lo, float hi) { unsigned r; asm volatile("v_cvt_pk_bf16_f32 %0, %1, %2" : "=v"(r) : "v"(lo), "v"(hi)); return r; }
; __device__ __forceinline__ float sigmoidf_(float x) { return __builtin_amdgcn_rcpf(1.0f + __expf(-x)); }
;     __device__ __forceinline__ void operator()(const f32x4 (&acc)[2][2][4][2], const Unit& u, int wr, int wc, int fr, int fq) const {
;     ...
;             for (int m = 0; m < 4; ++m) { const size_t row = (size_t)(row0 + ai * HALF + m * 16);
; #pragma unroll
;                 for (int bj = 0; bj < 2; ++bj) { const int c = col0 + bj * HALF;
;                     const u32x4 yv = *(const u32x4*)(Y + row * ldy + c);
;                     const f32x4 v0 = acc[ai][bj][m][0], v1 = acc[ai][bj][m][1];
;                     u32x4 w;
;                     w.x = cvt_pk_bf16(bflo(yv.x) * sigmoidf_(v0[0]), bfhi(yv.x) * sigmoidf_(v0[1]));
;                     w.y = cvt_pk_bf16(bflo(yv.y) * sigmoidf_(v0[2]), bfhi(yv.y) * sigmoidf_(v0[3]));
;                     w.z = cvt_pk_bf16(bflo(yv.z) * sigmoidf_(v1[0]), bfhi(yv.z) * sigmoidf_(v1[1]));
;                     w.w = cvt_pk_bf16(bflo(yv.w) * sigmoidf_(v1[2]), bfhi(yv.w) * sigmoidf_(v1[3]));
;                     *(u32x4*)(O + row * ldc + ocol0 + c) = w; } }
	v_lshlrev_b32_e32 v104, 16, v112
	v_and_b32_e32 v105, 0xffff0000, v112
	v_lshlrev_b32_e32 v123, 16, v115
	v_and_b32_e32 v115, 0xffff0000, v115
	v_lshlrev_b32_e32 v112, 16, v113
	v_and_b32_e32 v113, 0xffff0000, v113
	v_lshlrev_b32_e32 v122, 16, v114
	v_and_b32_e32 v114, 0xffff0000, v114
	v_mul_f32_e32 v104, v116, v104
	v_mul_f32_e32 v105, v117, v105
	v_mul_f32_e32 v107, v107, v115
	v_mul_f32_e32 v110, v110, v112
	v_mul_f32_e32 v111, v111, v113
	v_mul_f32_e32 v112, v120, v122
	v_mul_f32_e32 v113, v121, v114
	v_mul_f32_e32 v114, v106, v123
	v_cvt_pk_bf16_f32 v104, v104, v105
	v_cvt_pk_bf16_f32 v105, v110, v111
	v_cvt_pk_bf16_f32 v106, v112, v113
	v_cvt_pk_bf16_f32 v107, v114, v107
	global_store_dwordx4 v[108:109], v[104:107], off offset:2048
	v_exp_f32_e32 v110, v100
	v_exp_f32_e32 v111, v101
	v_add_u32_e32 v100, 32, v140
	v_ashrrev_i32_e32 v101, 31, v100
	v_add_f32_e32 v110, 1.0, v110
	v_add_f32_e32 v111, 1.0, v111
	v_add_f32_e32 v112, 1.0, v96
	v_add_f32_e32 v113, 1.0, v97
	v_rcp_f32_e32 v110, v110
	v_rcp_f32_e32 v111, v111
	v_lshlrev_b64 v[96:97], 10, v[100:101]
	v_rcp_f32_e32 v114, v102
	v_rcp_f32_e32 v115, v103
	v_rcp_f32_e32 v112, v112
	v_rcp_f32_e32 v113, v113
	v_lshl_add_u64 v[96:97], s[6:7], 0, v[96:97]
	v_lshl_add_u64 v[102:103], v[96:97], 0, v[138:139]
	v_add_f32_e32 v62, 1.0, v62
	v_add_f32_e32 v63, 1.0, v63
	v_add_f32_e32 v58, 1.0, v58
	v_rcp_f32_e32 v59, v59
	v_rcp_f32_e32 v62, v62
	v_rcp_f32_e32 v63, v63
	v_rcp_f32_e32 v58, v58
	v_mul_f32_e32 v52, 0xbfb8aa3b, v52
	v_mul_f32_e32 v53, 0xbfb8aa3b, v53
	v_mul_f32_e32 v51, 0xbfb8aa3b, v51
	v_mul_f32_e32 v54, 0xbfb8aa3b, v54
	v_mul_f32_e32 v55, 0xbfb8aa3b, v55
	v_mul_f32_e32 v48, 0xbfb8aa3b, v48
	v_mul_f32_e32 v49, 0xbfb8aa3b, v49
	v_mul_f32_e32 v50, 0xbfb8aa3b, v50
	v_exp_f32_e32 v51, v51
	v_exp_f32_e32 v54, v54
	v_exp_f32_e32 v55, v55
	v_exp_f32_e32 v48, v48
	v_exp_f32_e32 v49, v49
	v_exp_f32_e32 v50, v50
	v_add_f32_e32 v51, 1.0, v51
	v_add_f32_e32 v54, 1.0, v54
	v_add_f32_e32 v55, 1.0, v55
	v_add_f32_e32 v50, 1.0, v50
	v_rcp_f32_e32 v51, v51
	v_rcp_f32_e32 v50, v50
	v_mul_f32_e32 v44, 0xbfb8aa3b, v44
	v_mul_f32_e32 v45, 0xbfb8aa3b, v45
	v_mul_f32_e32 v43, 0xbfb8aa3b, v43
	v_mul_f32_e32 v46, 0xbfb8aa3b, v46
	v_mul_f32_e32 v47, 0xbfb8aa3b, v47
	v_mul_f32_e32 v40, 0xbfb8aa3b, v40
	v_mul_f32_e32 v41, 0xbfb8aa3b, v41
	v_mul_f32_e32 v42, 0xbfb8aa3b, v42
	v_exp_f32_e32 v44, v44
	v_exp_f32_e32 v45, v45
	v_exp_f32_e32 v43, v43
	v_exp_f32_e32 v46, v46
	v_exp_f32_e32 v47, v47
	v_exp_f32_e32 v40, v40
	v_exp_f32_e32 v41, v41
	v_exp_f32_e32 v42, v42
	v_add_f32_e32 v44, 1.0, v44
	v_add_f32_e32 v45, 1.0, v45
	v_add_f32_e32 v43, 1.0, v43
	v_add_f32_e32 v46, 1.0, v46
	v_add_f32_e32 v47, 1.0, v47
	v_add_f32_e32 v42, 1.0, v42
	v_rcp_f32_e32 v43, v43
	v_rcp_f32_e32 v46, v46
	v_rcp_f32_e32 v47, v47
	v_rcp_f32_e32 v42, v42
	v_mul_f32_e32 v36, 0xbfb8aa3b, v36
	v_mul_f32_e32 v37, 0xbfb8aa3b, v37
	v_mul_f32_e32 v35, 0xbfb8aa3b, v35
	v_mul_f32_e32 v38, 0xbfb8aa3b, v38
	v_mul_f32_e32 v39, 0xbfb8aa3b, v39
	v_mul_f32_e32 v32, 0xbfb8aa3b, v32
	v_mul_f32_e32 v33, 0xbfb8aa3b, v33
	v_mul_f32_e32 v34, 0xbfb8aa3b, v34
	v_exp_f32_e32 v35, v35
	s_waitcnt vmcnt(13)
	s_nop 1
	v_mov_b32_e32 v104, v172
	v_mov_b32_e32 v105, v173
	v_mov_b32_e32 v106, v174
	v_mov_b32_e32 v107, v175
	v_lshlrev_b32_e32 v96, 16, v104
	v_and_b32_e32 v97, 0xffff0000, v104
	v_lshlrev_b32_e32 v117, 16, v107
	v_and_b32_e32 v107, 0xffff0000, v107
	v_lshlrev_b32_e32 v104, 16, v105
	v_and_b32_e32 v105, 0xffff0000, v105
	v_lshlrev_b32_e32 v116, 16, v106
	v_and_b32_e32 v106, 0xffff0000, v106
	v_mul_f32_e32 v96, v110, v96
	v_mul_f32_e32 v97, v111, v97
	v_mul_f32_e32 v99, v99, v107
	v_mul_f32_e32 v104, v114, v104
	v_mul_f32_e32 v105, v115, v105
	v_mul_f32_e32 v110, v112, v116
	v_mul_f32_e32 v106, v113, v106
	v_mul_f32_e32 v111, v98, v117
	v_cvt_pk_bf16_f32 v96, v96, v97
	v_cvt_pk_bf16_f32 v97, v104, v105
	v_cvt_pk_bf16_f32 v98, v110, v106
	v_cvt_pk_bf16_f32 v99, v111, v99
	global_store_dwordx4 v[108:109], v[96:99], off offset:2304
	v_add_f32_e32 v104, 1.0, v88
	v_add_f32_e32 v105, 1.0, v89
	v_lshlrev_b64 v[88:89], 12, v[100:101]
	v_rcp_f32_e32 v100, v92
	v_rcp_f32_e32 v101, v93
	v_rcp_f32_e32 v104, v104
	v_rcp_f32_e32 v105, v105
	v_lshl_add_u64 v[88:89], s[8:9], 0, v[88:89]
	v_lshl_add_u64 v[92:93], v[88:89], 0, v[138:139]
	v_exp_f32_e32 v38, v38
	v_exp_f32_e32 v39, v39
	v_exp_f32_e32 v32, v32
	v_exp_f32_e32 v33, v33
	v_exp_f32_e32 v34, v34
	v_add_f32_e32 v35, 1.0, v35
	v_add_f32_e32 v38, 1.0, v38
	v_add_f32_e32 v39, 1.0, v39
	v_add_f32_e32 v34, 1.0, v34
	v_rcp_f32_e32 v35, v35
	v_rcp_f32_e32 v34, v34
	v_mul_f32_e32 v28, 0xbfb8aa3b, v28
	v_mul_f32_e32 v29, 0xbfb8aa3b, v29
	v_mul_f32_e32 v27, 0xbfb8aa3b, v27
	v_mul_f32_e32 v30, 0xbfb8aa3b, v30
	v_mul_f32_e32 v31, 0xbfb8aa3b, v31
	v_mul_f32_e32 v24, 0xbfb8aa3b, v24
	v_mul_f32_e32 v25, 0xbfb8aa3b, v25
	v_mul_f32_e32 v26, 0xbfb8aa3b, v26
	v_exp_f32_e32 v28, v28
	v_exp_f32_e32 v29, v29
	v_exp_f32_e32 v27, v27
	v_exp_f32_e32 v30, v30
	v_exp_f32_e32 v31, v31
	v_exp_f32_e32 v24, v24
	v_exp_f32_e32 v25, v25
	v_exp_f32_e32 v26, v26
	v_add_f32_e32 v28, 1.0, v28
	v_add_f32_e32 v29, 1.0, v29
	v_add_f32_e32 v27, 1.0, v27
	v_add_f32_e32 v30, 1.0, v30
	v_add_f32_e32 v31, 1.0, v31
	v_add_f32_e32 v26, 1.0, v26
	v_rcp_f32_e32 v27, v27
	v_rcp_f32_e32 v30, v30
	v_rcp_f32_e32 v31, v31
	v_rcp_f32_e32 v26, v26
	v_mul_f32_e32 v20, 0xbfb8aa3b, v20
	v_mul_f32_e32 v21, 0xbfb8aa3b, v21
	v_mul_f32_e32 v19, 0xbfb8aa3b, v19
	v_mul_f32_e32 v22, 0xbfb8aa3b, v22
	v_mul_f32_e32 v23, 0xbfb8aa3b, v23
	v_mul_f32_e32 v16, 0xbfb8aa3b, v16
	v_mul_f32_e32 v17, 0xbfb8aa3b, v17
	v_mul_f32_e32 v18, 0xbfb8aa3b, v18
	v_exp_f32_e32 v19, v19
	v_exp_f32_e32 v22, v22
	v_exp_f32_e32 v23, v23
	v_exp_f32_e32 v16, v16
	v_exp_f32_e32 v17, v17
	v_exp_f32_e32 v18, v18
	v_add_f32_e32 v19, 1.0, v19
	v_add_f32_e32 v22, 1.0, v22
	v_add_f32_e32 v23, 1.0, v23
	v_add_f32_e32 v18, 1.0, v18
	v_rcp_f32_e32 v19, v19
	v_rcp_f32_e32 v18, v18
	v_mul_f32_e32 v12, 0xbfb8aa3b, v12
	v_mul_f32_e32 v13, 0xbfb8aa3b, v13
	v_mul_f32_e32 v11, 0xbfb8aa3b, v11
	v_mul_f32_e32 v14, 0xbfb8aa3b, v14
	v_mul_f32_e32 v15, 0xbfb8aa3b, v15
	v_mul_f32_e32 v8, 0xbfb8aa3b, v8
	v_mul_f32_e32 v9, 0xbfb8aa3b, v9
	v_mul_f32_e32 v10, 0xbfb8aa3b, v10
	v_exp_f32_e32 v12, v12
	v_exp_f32_e32 v13, v13
	v_exp_f32_e32 v11, v11
	v_exp_f32_e32 v14, v14
	v_exp_f32_e32 v15, v15
	s_waitcnt vmcnt(13)
; __device__ __forceinline__ unsigned cvt_pk_bf16(float lo, float hi) { unsigned r; asm volatile("v_cvt_pk_bf16_f32 %0, %1, %2" : "=v"(r) : "v"(lo), "v"(hi)); return r; }
; __device__ __forceinline__ float sigmoidf_(float x) { return __builtin_amdgcn_rcpf(1.0f + __expf(-x)); }
;     __device__ __forceinline__ void operator()(const f32x4 (&acc)[2][2][4][2], const Unit& u, int wr, int wc, int fr, int fq) const {
;     ...
;             for (int m = 0; m < 4; ++m) { const size_t row = (size_t)(row0 + ai * HALF + m * 16);
; #pragma unroll
;                 for (int bj = 0; bj < 2; ++bj) { const int c = col0 + bj * HALF;
;                     const u32x4 yv = *(const u32x4*)(Y + row * ldy + c);
;                     const f32x4 v0 = acc[ai][bj][m][0], v1 = acc[ai][bj][m][1];
;                     u32x4 w;
;                     w.x = cvt_pk_bf16(bflo(yv.x) * sigmoidf_(v0[0]), bfhi(yv.x) * sigmoidf_(v0[1]));
;                     w.y = cvt_pk_bf16(bflo(yv.y) * sigmoidf_(v0[2]), bfhi(yv.y) * sigmoidf_(v0[3]));
;                     w.z = cvt_pk_bf16(bflo(yv.z) * sigmoidf_(v1[0]), bfhi(yv.z) * sigmoidf_(v1[1]));
;                     w.w = cvt_pk_bf16(bflo(yv.w) * sigmoidf_(v1[2]), bfhi(yv.w) * sigmoidf_(v1[3]));
;                     *(u32x4*)(O + row * ldc + ocol0 + c) = w; } }
	s_nop 1
	v_mov_b32_e32 v96, v176
	v_mov_b32_e32 v97, v177
	v_mov_b32_e32 v98, v178
	v_mov_b32_e32 v99, v179
	v_lshlrev_b32_e32 v88, 16, v96
	v_and_b32_e32 v89, 0xffff0000, v96
	v_lshlrev_b32_e32 v107, 16, v99
	v_and_b32_e32 v99, 0xffff0000, v99
	v_lshlrev_b32_e32 v96, 16, v97
	v_and_b32_e32 v97, 0xffff0000, v97
	v_lshlrev_b32_e32 v106, 16, v98
	v_and_b32_e32 v98, 0xffff0000, v98
	v_mul_f32_e32 v88, v100, v88
	v_mul_f32_e32 v89, v101, v89
	v_mul_f32_e32 v91, v91, v99
	v_mul_f32_e32 v94, v94, v96
	v_mul_f32_e32 v95, v95, v97
	v_mul_f32_e32 v96, v104, v106
	v_mul_f32_e32 v97, v105, v98
	v_mul_f32_e32 v98, v90, v107
	v_cvt_pk_bf16_f32 v88, v88, v89
	v_cvt_pk_bf16_f32 v89, v94, v95
	v_cvt_pk_bf16_f32 v90, v96, v97
	v_cvt_pk_bf16_f32 v91, v98, v91
	global_store_dwordx4 v[92:93], v[88:91], off offset:2048
	v_exp_f32_e32 v94, v84
	v_exp_f32_e32 v95, v85
	v_add_u32_e32 v84, 48, v140
	v_ashrrev_i32_e32 v85, 31, v84
	v_add_f32_e32 v94, 1.0, v94
	v_add_f32_e32 v95, 1.0, v95
	v_add_f32_e32 v96, 1.0, v80
	v_add_f32_e32 v97, 1.0, v81
	v_rcp_f32_e32 v94, v94
	v_rcp_f32_e32 v95, v95
	v_lshlrev_b64 v[80:81], 10, v[84:85]
	v_rcp_f32_e32 v98, v86
	v_rcp_f32_e32 v99, v87
	v_rcp_f32_e32 v96, v96
	v_rcp_f32_e32 v97, v97
	v_lshl_add_u64 v[80:81], s[6:7], 0, v[80:81]
	v_lshl_add_u64 v[86:87], v[80:81], 0, v[138:139]
	v_exp_f32_e32 v8, v8
	v_exp_f32_e32 v9, v9
	v_exp_f32_e32 v10, v10
	v_add_f32_e32 v12, 1.0, v12
	v_add_f32_e32 v13, 1.0, v13
	v_add_f32_e32 v11, 1.0, v11
	v_add_f32_e32 v14, 1.0, v14
	v_add_f32_e32 v15, 1.0, v15
	v_add_f32_e32 v10, 1.0, v10
	v_rcp_f32_e32 v11, v11
	v_rcp_f32_e32 v14, v14
	v_rcp_f32_e32 v15, v15
	v_rcp_f32_e32 v10, v10
	v_mul_f32_e32 v3, 0xbfb8aa3b, v3
	v_mul_f32_e32 v4, 0xbfb8aa3b, v4
	v_mul_f32_e32 v5, 0xbfb8aa3b, v5
	v_mul_f32_e32 v6, 0xbfb8aa3b, v6
	v_mul_f32_e32 v7, 0xbfb8aa3b, v7
	v_mul_f32_e32 v0, 0xbfb8aa3b, v0
	v_mul_f32_e32 v1, 0xbfb8aa3b, v1
	v_mul_f32_e32 v2, 0xbfb8aa3b, v2
	v_exp_f32_e32 v3, v3
	v_exp_f32_e32 v4, v4
	v_exp_f32_e32 v5, v5
	v_exp_f32_e32 v6, v6
	v_exp_f32_e32 v7, v7
	v_exp_f32_e32 v0, v0
	v_exp_f32_e32 v1, v1
	v_exp_f32_e32 v2, v2
	v_add_f32_e32 v3, 1.0, v3
	v_add_f32_e32 v4, 1.0, v4
	v_add_f32_e32 v5, 1.0, v5
	v_add_f32_e32 v6, 1.0, v6
	v_add_f32_e32 v7, 1.0, v7
	v_add_f32_e32 v0, 1.0, v0
	v_add_f32_e32 v1, 1.0, v1
	v_add_f32_e32 v2, 1.0, v2
	v_rcp_f32_e32 v3, v3
	v_rcp_f32_e32 v4, v4
	v_rcp_f32_e32 v5, v5
	v_rcp_f32_e32 v6, v6
	v_rcp_f32_e32 v7, v7
	v_rcp_f32_e32 v0, v0
	v_rcp_f32_e32 v1, v1
	v_rcp_f32_e32 v2, v2
	s_andn2_b64 vcc, exec, s[0:1]
	s_mov_b64 s[0:1], -1
	s_waitcnt vmcnt(13)
	s_nop 1
	v_mov_b32_e32 v88, v180
	v_mov_b32_e32 v89, v181
	v_mov_b32_e32 v90, v182
	v_mov_b32_e32 v91, v183
	v_lshlrev_b32_e32 v80, 16, v88
	v_and_b32_e32 v81, 0xffff0000, v88
	v_lshlrev_b32_e32 v101, 16, v91
	v_and_b32_e32 v91, 0xffff0000, v91
	v_lshlrev_b32_e32 v88, 16, v89
	v_and_b32_e32 v89, 0xffff0000, v89
	v_lshlrev_b32_e32 v100, 16, v90
	v_and_b32_e32 v90, 0xffff0000, v90
	v_mul_f32_e32 v80, v94, v80
	v_mul_f32_e32 v81, v95, v81
	v_mul_f32_e32 v83, v83, v91
	v_mul_f32_e32 v88, v98, v88
	v_mul_f32_e32 v89, v99, v89
	v_mul_f32_e32 v94, v96, v100
	v_mul_f32_e32 v90, v97, v90
	v_mul_f32_e32 v95, v82, v101
	v_cvt_pk_bf16_f32 v80, v80, v81
	v_cvt_pk_bf16_f32 v81, v88, v89
	v_cvt_pk_bf16_f32 v82, v94, v90
	v_cvt_pk_bf16_f32 v83, v95, v83
	global_store_dwordx4 v[92:93], v[80:83], off offset:2304
	v_add_f32_e32 v88, 1.0, v72
	v_add_f32_e32 v89, 1.0, v73
	v_lshlrev_b64 v[72:73], 12, v[84:85]
	v_rcp_f32_e32 v84, v76
	v_rcp_f32_e32 v85, v77
	v_rcp_f32_e32 v88, v88
	v_rcp_f32_e32 v89, v89
	v_lshl_add_u64 v[72:73], s[8:9], 0, v[72:73]
	v_lshl_add_u64 v[76:77], v[72:73], 0, v[138:139]
	s_waitcnt vmcnt(13)
	s_nop 1
	v_mov_b32_e32 v80, v184
	v_mov_b32_e32 v81, v185
	v_mov_b32_e32 v82, v186
	v_mov_b32_e32 v83, v187
	v_lshlrev_b32_e32 v72, 16, v80
	v_and_b32_e32 v73, 0xffff0000, v80
	v_lshlrev_b32_e32 v91, 16, v83
	v_and_b32_e32 v83, 0xffff0000, v83
	v_lshlrev_b32_e32 v80, 16, v81
	v_and_b32_e32 v81, 0xffff0000, v81
	v_lshlrev_b32_e32 v90, 16, v82
	v_and_b32_e32 v82, 0xffff0000, v82
	v_mul_f32_e32 v72, v84, v72
	v_mul_f32_e32 v73, v85, v73
	v_mul_f32_e32 v75, v75, v83
	v_mul_f32_e32 v78, v78, v80
	v_mul_f32_e32 v79, v79, v81
	v_mul_f32_e32 v80, v88, v90
	v_mul_f32_e32 v81, v89, v82
	v_mul_f32_e32 v82, v74, v91
	v_cvt_pk_bf16_f32 v72, v72, v73
	v_cvt_pk_bf16_f32 v73, v78, v79
	v_cvt_pk_bf16_f32 v74, v80, v81
	v_cvt_pk_bf16_f32 v75, v82, v75
	global_store_dwordx4 v[76:77], v[72:75], off offset:2048
	v_exp_f32_e32 v78, v68
	v_exp_f32_e32 v79, v69
	v_add_u32_e32 v68, 0x80, v140
	v_ashrrev_i32_e32 v69, 31, v68
	v_add_f32_e32 v78, 1.0, v78
	v_add_f32_e32 v79, 1.0, v79
	v_add_f32_e32 v80, 1.0, v64
	v_add_f32_e32 v81, 1.0, v65
	v_rcp_f32_e32 v78, v78
	v_rcp_f32_e32 v79, v79
	v_lshlrev_b64 v[64:65], 10, v[68:69]
	v_rcp_f32_e32 v82, v70
	v_rcp_f32_e32 v83, v71
	v_rcp_f32_e32 v80, v80
	v_rcp_f32_e32 v81, v81
	v_lshl_add_u64 v[64:65], s[6:7], 0, v[64:65]
	v_lshl_add_u64 v[70:71], v[64:65], 0, v[138:139]
	s_waitcnt vmcnt(13)
	s_nop 1
	v_mov_b32_e32 v72, v188
	v_mov_b32_e32 v73, v189
	v_mov_b32_e32 v74, v190
	v_mov_b32_e32 v75, v191
	v_lshlrev_b32_e32 v64, 16, v72
	v_and_b32_e32 v65, 0xffff0000, v72
	v_lshlrev_b32_e32 v85, 16, v75
	v_and_b32_e32 v75, 0xffff0000, v75
	v_lshlrev_b32_e32 v72, 16, v73
	v_and_b32_e32 v73, 0xffff0000, v73
	v_lshlrev_b32_e32 v84, 16, v74
	v_and_b32_e32 v74, 0xffff0000, v74
	v_mul_f32_e32 v64, v78, v64
	v_mul_f32_e32 v65, v79, v65
	v_mul_f32_e32 v67, v67, v75
	v_mul_f32_e32 v72, v82, v72
	v_mul_f32_e32 v73, v83, v73
	v_mul_f32_e32 v78, v80, v84
	v_mul_f32_e32 v74, v81, v74
	v_mul_f32_e32 v79, v66, v85
	v_cvt_pk_bf16_f32 v64, v64, v65
	v_cvt_pk_bf16_f32 v65, v72, v73
	v_cvt_pk_bf16_f32 v66, v78, v74
	v_cvt_pk_bf16_f32 v67, v79, v67
	global_store_dwordx4 v[76:77], v[64:67], off offset:2304
	v_add_f32_e32 v72, 1.0, v56
	v_add_f32_e32 v73, 1.0, v57
	v_lshlrev_b64 v[56:57], 12, v[68:69]
	v_rcp_f32_e32 v68, v60
	v_rcp_f32_e32 v69, v61
	v_rcp_f32_e32 v72, v72
	v_rcp_f32_e32 v73, v73
	v_lshl_add_u64 v[56:57], s[8:9], 0, v[56:57]
	v_lshl_add_u64 v[60:61], v[56:57], 0, v[138:139]
	s_waitcnt vmcnt(13)
; __device__ __forceinline__ unsigned cvt_pk_bf16(float lo, float hi) { unsigned r; asm volatile("v_cvt_pk_bf16_f32 %0, %1, %2" : "=v"(r) : "v"(lo), "v"(hi)); return r; }
; __device__ __forceinline__ float sigmoidf_(float x) { return __builtin_amdgcn_rcpf(1.0f + __expf(-x)); }
;     __device__ __forceinline__ void operator()(const f32x4 (&acc)[2][2][4][2], const Unit& u, int wr, int wc, int fr, int fq) const {
;     ...
;             for (int m = 0; m < 4; ++m) { const size_t row = (size_t)(row0 + ai * HALF + m * 16);
; #pragma unroll
;                 for (int bj = 0; bj < 2; ++bj) { const int c = col0 + bj * HALF;
;                     const u32x4 yv = *(const u32x4*)(Y + row * ldy + c);
;                     const f32x4 v0 = acc[ai][bj][m][0], v1 = acc[ai][bj][m][1];
;                     u32x4 w;
;                     w.x = cvt_pk_bf16(bflo(yv.x) * sigmoidf_(v0[0]), bfhi(yv.x) * sigmoidf_(v0[1]));
;                     w.y = cvt_pk_bf16(bflo(yv.y) * sigmoidf_(v0[2]), bfhi(yv.y) * sigmoidf_(v0[3]));
;                     w.z = cvt_pk_bf16(bflo(yv.z) * sigmoidf_(v1[0]), bfhi(yv.z) * sigmoidf_(v1[1]));
;                     w.w = cvt_pk_bf16(bflo(yv.w) * sigmoidf_(v1[2]), bfhi(yv.w) * sigmoidf_(v1[3]));
;                     *(u32x4*)(O + row * ldc + ocol0 + c) = w; } }
	s_nop 1
	v_mov_b32_e32 v64, v200
	v_mov_b32_e32 v65, v201
	v_mov_b32_e32 v66, v202
	v_mov_b32_e32 v67, v203
	v_lshlrev_b32_e32 v56, 16, v64
	v_and_b32_e32 v57, 0xffff0000, v64
	v_lshlrev_b32_e32 v75, 16, v67
	v_and_b32_e32 v67, 0xffff0000, v67
	v_lshlrev_b32_e32 v64, 16, v65
	v_and_b32_e32 v65, 0xffff0000, v65
	v_lshlrev_b32_e32 v74, 16, v66
	v_and_b32_e32 v66, 0xffff0000, v66
	v_mul_f32_e32 v56, v68, v56
	v_mul_f32_e32 v57, v69, v57
	v_mul_f32_e32 v59, v59, v67
	v_mul_f32_e32 v62, v62, v64
	v_mul_f32_e32 v63, v63, v65
	v_mul_f32_e32 v64, v72, v74
	v_mul_f32_e32 v65, v73, v66
	v_mul_f32_e32 v66, v58, v75
	v_cvt_pk_bf16_f32 v56, v56, v57
	v_cvt_pk_bf16_f32 v57, v62, v63
	v_cvt_pk_bf16_f32 v58, v64, v65
	v_cvt_pk_bf16_f32 v59, v66, v59
	global_store_dwordx4 v[60:61], v[56:59], off offset:2048
	v_exp_f32_e32 v62, v52
	v_exp_f32_e32 v63, v53
	v_add_u32_e32 v52, 0x90, v140
	v_ashrrev_i32_e32 v53, 31, v52
	v_add_f32_e32 v62, 1.0, v62
	v_add_f32_e32 v63, 1.0, v63
	v_add_f32_e32 v64, 1.0, v48
	v_add_f32_e32 v65, 1.0, v49
	v_rcp_f32_e32 v62, v62
	v_rcp_f32_e32 v63, v63
	v_lshlrev_b64 v[48:49], 10, v[52:53]
	v_rcp_f32_e32 v66, v54
	v_rcp_f32_e32 v67, v55
	v_rcp_f32_e32 v64, v64
	v_rcp_f32_e32 v65, v65
	v_lshl_add_u64 v[48:49], s[6:7], 0, v[48:49]
	v_lshl_add_u64 v[54:55], v[48:49], 0, v[138:139]
	s_waitcnt vmcnt(13)
	s_nop 1
	v_mov_b32_e32 v56, v204
	v_mov_b32_e32 v57, v205
	v_mov_b32_e32 v58, v206
	v_mov_b32_e32 v59, v207
	v_lshlrev_b32_e32 v48, 16, v56
	v_and_b32_e32 v49, 0xffff0000, v56
	v_lshlrev_b32_e32 v69, 16, v59
	v_and_b32_e32 v59, 0xffff0000, v59
	v_lshlrev_b32_e32 v56, 16, v57
	v_and_b32_e32 v57, 0xffff0000, v57
	v_lshlrev_b32_e32 v68, 16, v58
	v_and_b32_e32 v58, 0xffff0000, v58
	v_mul_f32_e32 v48, v62, v48
	v_mul_f32_e32 v49, v63, v49
	v_mul_f32_e32 v51, v51, v59
	v_mul_f32_e32 v56, v66, v56
	v_mul_f32_e32 v57, v67, v57
	v_mul_f32_e32 v62, v64, v68
	v_mul_f32_e32 v58, v65, v58
	v_mul_f32_e32 v63, v50, v69
	v_cvt_pk_bf16_f32 v48, v48, v49
	v_cvt_pk_bf16_f32 v49, v56, v57
	v_cvt_pk_bf16_f32 v50, v62, v58
	v_cvt_pk_bf16_f32 v51, v63, v51
	global_store_dwordx4 v[60:61], v[48:51], off offset:2304
	v_add_f32_e32 v56, 1.0, v40
	v_add_f32_e32 v57, 1.0, v41
	v_lshlrev_b64 v[40:41], 12, v[52:53]
	v_rcp_f32_e32 v52, v44
	v_rcp_f32_e32 v53, v45
	v_rcp_f32_e32 v56, v56
	v_rcp_f32_e32 v57, v57
	v_lshl_add_u64 v[40:41], s[8:9], 0, v[40:41]
	v_lshl_add_u64 v[44:45], v[40:41], 0, v[138:139]
	s_waitcnt vmcnt(13)
	s_nop 1
	v_mov_b32_e32 v48, v208
	v_mov_b32_e32 v49, v209
	v_mov_b32_e32 v50, v210
	v_mov_b32_e32 v51, v211
	v_lshlrev_b32_e32 v40, 16, v48
	v_and_b32_e32 v41, 0xffff0000, v48
	v_lshlrev_b32_e32 v59, 16, v51
	v_and_b32_e32 v51, 0xffff0000, v51
	v_lshlrev_b32_e32 v48, 16, v49
	v_and_b32_e32 v49, 0xffff0000, v49
	v_lshlrev_b32_e32 v58, 16, v50
	v_and_b32_e32 v50, 0xffff0000, v50
	v_mul_f32_e32 v40, v52, v40
	v_mul_f32_e32 v41, v53, v41
	v_mul_f32_e32 v43, v43, v51
	v_mul_f32_e32 v46, v46, v48
	v_mul_f32_e32 v47, v47, v49
	v_mul_f32_e32 v48, v56, v58
	v_mul_f32_e32 v49, v57, v50
	v_mul_f32_e32 v50, v42, v59
	v_cvt_pk_bf16_f32 v40, v40, v41
	v_cvt_pk_bf16_f32 v41, v46, v47
	v_cvt_pk_bf16_f32 v42, v48, v49
	v_cvt_pk_bf16_f32 v43, v50, v43
	global_store_dwordx4 v[44:45], v[40:43], off offset:2048
	v_exp_f32_e32 v46, v36
	v_exp_f32_e32 v47, v37
	v_add_u32_e32 v36, 0xa0, v140
	v_ashrrev_i32_e32 v37, 31, v36
	v_add_f32_e32 v46, 1.0, v46
	v_add_f32_e32 v47, 1.0, v47
	v_add_f32_e32 v48, 1.0, v32
	v_add_f32_e32 v49, 1.0, v33
	v_rcp_f32_e32 v46, v46
	v_rcp_f32_e32 v47, v47
	v_lshlrev_b64 v[32:33], 10, v[36:37]
	v_rcp_f32_e32 v50, v38
	v_rcp_f32_e32 v51, v39
	v_rcp_f32_e32 v48, v48
	v_rcp_f32_e32 v49, v49
	v_lshl_add_u64 v[32:33], s[6:7], 0, v[32:33]
	v_lshl_add_u64 v[38:39], v[32:33], 0, v[138:139]
	s_waitcnt vmcnt(13)
	s_nop 1
	v_mov_b32_e32 v40, v212
	v_mov_b32_e32 v41, v213
	v_mov_b32_e32 v42, v214
	v_mov_b32_e32 v43, v215
	v_lshlrev_b32_e32 v32, 16, v40
	v_and_b32_e32 v33, 0xffff0000, v40
	v_lshlrev_b32_e32 v53, 16, v43
	v_and_b32_e32 v43, 0xffff0000, v43
	v_lshlrev_b32_e32 v40, 16, v41
	v_and_b32_e32 v41, 0xffff0000, v41
	v_lshlrev_b32_e32 v52, 16, v42
	v_and_b32_e32 v42, 0xffff0000, v42
	v_mul_f32_e32 v32, v46, v32
	v_mul_f32_e32 v33, v47, v33
	v_mul_f32_e32 v35, v35, v43
	v_mul_f32_e32 v40, v50, v40
	v_mul_f32_e32 v41, v51, v41
	v_mul_f32_e32 v46, v48, v52
	v_mul_f32_e32 v42, v49, v42
	v_mul_f32_e32 v47, v34, v53
	v_cvt_pk_bf16_f32 v32, v32, v33
	v_cvt_pk_bf16_f32 v33, v40, v41
	v_cvt_pk_bf16_f32 v34, v46, v42
	v_cvt_pk_bf16_f32 v35, v47, v35
	global_store_dwordx4 v[44:45], v[32:35], off offset:2304
	v_add_f32_e32 v40, 1.0, v24
	v_add_f32_e32 v41, 1.0, v25
	v_lshlrev_b64 v[24:25], 12, v[36:37]
	v_rcp_f32_e32 v36, v28
	v_rcp_f32_e32 v37, v29
	v_rcp_f32_e32 v40, v40
	v_rcp_f32_e32 v41, v41
	v_lshl_add_u64 v[24:25], s[8:9], 0, v[24:25]
	v_lshl_add_u64 v[28:29], v[24:25], 0, v[138:139]
	s_waitcnt vmcnt(13)
; __device__ __forceinline__ unsigned cvt_pk_bf16(float lo, float hi) { unsigned r; asm volatile("v_cvt_pk_bf16_f32 %0, %1, %2" : "=v"(r) : "v"(lo), "v"(hi)); return r; }
; __device__ __forceinline__ float sigmoidf_(float x) { return __builtin_amdgcn_rcpf(1.0f + __expf(-x)); }
;     __device__ __forceinline__ void operator()(const f32x4 (&acc)[2][2][4][2], const Unit& u, int wr, int wc, int fr, int fq) const {
;     ...
;             for (int m = 0; m < 4; ++m) { const size_t row = (size_t)(row0 + ai * HALF + m * 16);
; #pragma unroll
;                 for (int bj = 0; bj < 2; ++bj) { const int c = col0 + bj * HALF;
;                     const u32x4 yv = *(const u32x4*)(Y + row * ldy + c);
;                     const f32x4 v0 = acc[ai][bj][m][0], v1 = acc[ai][bj][m][1];
;                     u32x4 w;
;                     w.x = cvt_pk_bf16(bflo(yv.x) * sigmoidf_(v0[0]), bfhi(yv.x) * sigmoidf_(v0[1]));
;                     w.y = cvt_pk_bf16(bflo(yv.y) * sigmoidf_(v0[2]), bfhi(yv.y) * sigmoidf_(v0[3]));
;                     w.z = cvt_pk_bf16(bflo(yv.z) * sigmoidf_(v1[0]), bfhi(yv.z) * sigmoidf_(v1[1]));
;                     w.w = cvt_pk_bf16(bflo(yv.w) * sigmoidf_(v1[2]), bfhi(yv.w) * sigmoidf_(v1[3]));
;                     *(u32x4*)(O + row * ldc + ocol0 + c) = w; } }
	s_nop 1
	v_mov_b32_e32 v32, v216
	v_mov_b32_e32 v33, v217
	v_mov_b32_e32 v34, v218
	v_mov_b32_e32 v35, v219
	v_lshlrev_b32_e32 v24, 16, v32
	v_and_b32_e32 v25, 0xffff0000, v32
	v_lshlrev_b32_e32 v43, 16, v35
	v_and_b32_e32 v35, 0xffff0000, v35
	v_lshlrev_b32_e32 v32, 16, v33
	v_and_b32_e32 v33, 0xffff0000, v33
	v_lshlrev_b32_e32 v42, 16, v34
	v_and_b32_e32 v34, 0xffff0000, v34
	v_mul_f32_e32 v24, v36, v24
	v_mul_f32_e32 v25, v37, v25
	v_mul_f32_e32 v27, v27, v35
	v_mul_f32_e32 v30, v30, v32
	v_mul_f32_e32 v31, v31, v33
	v_mul_f32_e32 v32, v40, v42
	v_mul_f32_e32 v33, v41, v34
	v_mul_f32_e32 v34, v26, v43
	v_cvt_pk_bf16_f32 v24, v24, v25
	v_cvt_pk_bf16_f32 v25, v30, v31
	v_cvt_pk_bf16_f32 v26, v32, v33
	v_cvt_pk_bf16_f32 v27, v34, v27
	global_store_dwordx4 v[28:29], v[24:27], off offset:2048
	v_exp_f32_e32 v30, v20
	v_exp_f32_e32 v31, v21
	v_add_u32_e32 v20, 0xb0, v140
	v_ashrrev_i32_e32 v21, 31, v20
	v_add_f32_e32 v30, 1.0, v30
	v_add_f32_e32 v31, 1.0, v31
	v_add_f32_e32 v32, 1.0, v16
	v_add_f32_e32 v33, 1.0, v17
	v_rcp_f32_e32 v30, v30
	v_rcp_f32_e32 v31, v31
	v_lshlrev_b64 v[16:17], 10, v[20:21]
	v_rcp_f32_e32 v34, v22
	v_rcp_f32_e32 v35, v23
	v_rcp_f32_e32 v32, v32
	v_rcp_f32_e32 v33, v33
	v_lshl_add_u64 v[16:17], s[6:7], 0, v[16:17]
	v_lshl_add_u64 v[22:23], v[16:17], 0, v[138:139]
	s_waitcnt vmcnt(13)
	s_nop 1
	v_mov_b32_e32 v24, v220
	v_mov_b32_e32 v25, v221
	v_mov_b32_e32 v26, v222
	v_mov_b32_e32 v27, v223
	v_lshlrev_b32_e32 v16, 16, v24
	v_and_b32_e32 v17, 0xffff0000, v24
	v_lshlrev_b32_e32 v37, 16, v27
	v_and_b32_e32 v27, 0xffff0000, v27
	v_lshlrev_b32_e32 v24, 16, v25
	v_and_b32_e32 v25, 0xffff0000, v25
	v_lshlrev_b32_e32 v36, 16, v26
	v_and_b32_e32 v26, 0xffff0000, v26
	v_mul_f32_e32 v16, v30, v16
	v_mul_f32_e32 v17, v31, v17
	v_mul_f32_e32 v19, v19, v27
	v_mul_f32_e32 v24, v34, v24
	v_mul_f32_e32 v25, v35, v25
	v_mul_f32_e32 v30, v32, v36
	v_mul_f32_e32 v26, v33, v26
	v_mul_f32_e32 v31, v18, v37
	v_cvt_pk_bf16_f32 v16, v16, v17
	v_cvt_pk_bf16_f32 v17, v24, v25
	v_cvt_pk_bf16_f32 v18, v30, v26
	v_cvt_pk_bf16_f32 v19, v31, v19
	global_store_dwordx4 v[28:29], v[16:19], off offset:2304
	v_add_f32_e32 v24, 1.0, v8
	v_add_f32_e32 v25, 1.0, v9
	v_lshlrev_b64 v[8:9], 12, v[20:21]
	v_rcp_f32_e32 v20, v12
	v_rcp_f32_e32 v21, v13
	v_rcp_f32_e32 v24, v24
	v_rcp_f32_e32 v25, v25
	v_lshl_add_u64 v[8:9], s[8:9], 0, v[8:9]
	v_lshl_add_u64 v[12:13], v[8:9], 0, v[138:139]
	s_waitcnt vmcnt(13)
	s_nop 1
	v_mov_b32_e32 v16, v224
	v_mov_b32_e32 v17, v225
	v_mov_b32_e32 v18, v226
	v_mov_b32_e32 v19, v227
	v_lshlrev_b32_e32 v8, 16, v16
	v_and_b32_e32 v9, 0xffff0000, v16
	v_lshlrev_b32_e32 v27, 16, v19
	v_and_b32_e32 v19, 0xffff0000, v19
	v_lshlrev_b32_e32 v16, 16, v17
	v_and_b32_e32 v17, 0xffff0000, v17
	v_lshlrev_b32_e32 v26, 16, v18
	v_and_b32_e32 v18, 0xffff0000, v18
	v_mul_f32_e32 v8, v20, v8
	v_mul_f32_e32 v9, v21, v9
	v_mul_f32_e32 v11, v11, v19
	v_mul_f32_e32 v14, v14, v16
	v_mul_f32_e32 v15, v15, v17
	v_mul_f32_e32 v16, v24, v26
	v_mul_f32_e32 v17, v25, v18
	v_mul_f32_e32 v18, v10, v27
	v_cvt_pk_bf16_f32 v8, v8, v9
	v_cvt_pk_bf16_f32 v9, v14, v15
	v_cvt_pk_bf16_f32 v10, v16, v17
	v_cvt_pk_bf16_f32 v11, v18, v11
	global_store_dwordx4 v[12:13], v[8:11], off offset:2048
	s_waitcnt vmcnt(13)
	s_nop 1
	v_mov_b32_e32 v8, v228
	v_mov_b32_e32 v9, v229
	v_mov_b32_e32 v10, v230
	v_mov_b32_e32 v11, v231
	v_lshlrev_b32_e32 v17, 16, v11
	v_and_b32_e32 v11, 0xffff0000, v11
	v_lshlrev_b32_e32 v14, 16, v8
	v_and_b32_e32 v8, 0xffff0000, v8
	v_lshlrev_b32_e32 v15, 16, v9
	v_and_b32_e32 v9, 0xffff0000, v9
	v_lshlrev_b32_e32 v16, 16, v10
	v_and_b32_e32 v10, 0xffff0000, v10
	v_mul_f32_e32 v3, v3, v11
	v_mul_f32_e32 v4, v4, v14
	v_mul_f32_e32 v5, v5, v8
	v_mul_f32_e32 v6, v6, v15
	v_mul_f32_e32 v7, v7, v9
	v_mul_f32_e32 v8, v0, v16
	v_mul_f32_e32 v9, v1, v10
	v_mul_f32_e32 v10, v2, v17
	v_cvt_pk_bf16_f32 v0, v4, v5
	v_cvt_pk_bf16_f32 v1, v6, v7
	v_cvt_pk_bf16_f32 v2, v8, v9
	v_cvt_pk_bf16_f32 v3, v10, v3
	global_store_dwordx4 v[12:13], v[0:3], off offset:2304
	s_cbranch_vccnz .LBB0_387
	s_andn2_b64 vcc, exec, s[4:5]
	s_cbranch_vccnz .LBB0_386
	s_barrier
	s_branch .LBB0_386
